# v85 with the w_in GEMM K-loop head moved 16 bytes (4 s_nop before the loop, 12 after its back edge; later code keeps its placement)
# baseline (speedup 1.0000x reference)
; #define PG8_STAGE(bufoff, gbase, voff) do { _Pragma("unroll") for (int _i = 0; _i < 2; ++_i) \
;         __builtin_amdgcn_global_load_lds((const unsigned*)((const char*)(gbase) + (voff)[_i]), (LAS unsigned*)(lds + (bufoff) + ldsw + _i * 8192), 16, 0, 0); } while (0)
; #define PG8_LDA(dst, b, h) do { _Pragma("unroll") for (int m = 0; m < 4; ++m) _Pragma("unroll") for (int k = 0; k < 2; ++k) dst[m][k] = *(const LAS bf16x8*)(lds + PG8_SA(b, h) + aoff + m * 2048 + k * 1024); } while (0)
; #define PG8_LDB(dst, b, h) do { _Pragma("unroll") for (int n = 0; n < 2; ++n) _Pragma("unroll") for (int k = 0; k < 2; ++k) dst[n][k] = *(const LAS bf16x8*)(lds + PG8_SB(b, h) + boff + n * 2048 + k * 1024); } while (0)
; #define PG8_MMA(ai, bj, At, Bt) do { __builtin_amdgcn_s_setprio(1); _Pragma("unroll") for (int m = 0; m < 4; ++m) _Pragma("unroll") for (int n = 0; n < 2; ++n) _Pragma("unroll") for (int k = 0; k < 2; ++k) \
;         acc[ai][bj][m][n] = __builtin_amdgcn_mfma_f32_16x16x32_bf16(Bt[n][k], At[m][k], acc[ai][bj][m][n], 0, 0, 0); __builtin_amdgcn_s_setprio(0); } while (0)
; #define PG8_WAIT_V(n) asm volatile("s_waitcnt vmcnt(" #n ")" ::: "memory")
; #define PG8_WAIT_L(n) asm volatile("s_waitcnt lgkmcnt(" #n ")" ::: "memory")
; #define PG8_BAR __builtin_amdgcn_s_barrier()
; #define PG8_SCHED __builtin_amdgcn_sched_barrier(0)
;     ...
;         for (int t = 0; t < nt; t += 2) {
;             const bool last = (t == nt - 2);
;             const char* a1 = cA + (size_t)(t + 1) * kstep;
;             const char* a2 = last ? nA : cA + (size_t)(t + 2) * kstep; const char* b2 = last ? nB : cB + (size_t)(t + 2) * kstep;
;             const char* a3 = a2 + kstep; const char* b3 = b2 + kstep;
;             PG8_LDB(B0, 0, 0); PG8_LDB(B1, 0, 1); PG8_SCHED; PG8_LDA(At, 0, 0); PG8_STAGE(PG8_SA(1, 1), a1 + hstepA, voffA);
;             PG8_WAIT_V(8); PG8_WAIT_L(0); PG8_BAR; PG8_MMA(0, 0, At, B0); PG8_MMA(0, 1, At, B1); PG8_BAR; PG8_SCHED;
;             PG8_LDA(At, 0, 1); PG8_STAGE(PG8_SB(0, 0), b2, voffB); PG8_STAGE(PG8_SB(0, 1), b2 + hstepB, voffB); PG8_STAGE(PG8_SA(0, 0), a2, voffA);
;             PG8_WAIT_V(8); PG8_WAIT_L(0); PG8_BAR; PG8_MMA(1, 0, At, B0); PG8_MMA(1, 1, At, B1); PG8_BAR; PG8_SCHED;
.LBB0_307:
	s_ashr_i32 s15, s14, 31
	s_lshl_b64 s[18:19], s[14:15], 20
	s_add_u32 s18, s30, s18
	s_addc_u32 s19, s31, s19
	s_ashr_i32 s13, s12, 31
	s_lshl_b64 s[20:21], s[12:13], 20
	s_add_u32 s20, s34, s20
	s_addc_u32 s21, s35, s21
	s_andn2_b64 vcc, exec, s[8:9]
	s_cbranch_vccnz .LBB0_311
	s_and_b64 s[26:27], s[4:5], exec
	s_cselect_b32 s13, s19, s25
	s_cselect_b32 s15, s18, s24
	s_cselect_b32 s48, s21, s23
	s_cselect_b32 s49, s20, s22
	s_add_u32 s50, s22, 0x100
	s_addc_u32 s51, s23, 0
	s_add_u32 s22, s24, 0x80080
	s_addc_u32 s23, s25, 0
	s_mov_b32 s24, 0
	s_nop 0
	s_nop 0
	s_nop 0
	s_nop 0
.LBB0_309:
	s_add_i32 s52, s24, 2
	s_add_u32 s25, s22, 0xfff80080
	s_addc_u32 s26, s23, -1
	s_add_i32 s53, 0, 0x10000
	s_cmp_eq_u32 s45, s24
	s_cselect_b32 s27, s13, s26
	s_cselect_b32 s26, s15, s25
	v_add_u32_e32 v147, s53, v129
	s_cselect_b32 s25, s48, s51
	s_cselect_b32 s24, s49, s50
	s_add_i32 s58, 0, 0x14000
	ds_read_b128 v[148:151], v147
	ds_read_b128 v[152:155], v147 offset:1024
	ds_read_b128 v[156:159], v147 offset:2048
	ds_read_b128 v[160:163], v147 offset:3072
	v_add_u32_e32 v147, s58, v129
	ds_read_b128 v[164:167], v147
	ds_read_b128 v[168:171], v147 offset:1024
	ds_read_b128 v[172:175], v147 offset:2048
	ds_read_b128 v[176:179], v147 offset:3072
	v_lshl_add_u64 v[220:221], s[22:23], 0, v[144:145]
	s_add_i32 m0, s17, 0xc000
	ds_read_b128 v[180:183], v146
	ds_read_b128 v[184:187], v146 offset:1024
	ds_read_b128 v[188:191], v146 offset:2048
	ds_read_b128 v[198:201], v146 offset:3072
	ds_read_b128 v[202:205], v146 offset:4096
	ds_read_b128 v[206:209], v146 offset:5120
	ds_read_b128 v[210:213], v146 offset:6144
	ds_read_b128 v[230:233], v146 offset:7168
	global_load_lds_dwordx4 v[220:221], off
	v_lshl_add_u64 v[220:221], s[22:23], 0, v[142:143]
	s_add_i32 m0, s17, 0xe000
	s_nop 0
	global_load_lds_dwordx4 v[220:221], off
	s_waitcnt vmcnt(8)
	s_waitcnt lgkmcnt(0)
	s_barrier
	s_setprio 1
	s_waitcnt lgkmcnt(0)
	v_mfma_f32_16x16x32_bf16 v[68:71], v[148:151], v[180:183], v[68:71]
	v_mfma_f32_16x16x32_bf16 v[76:79], v[156:159], v[180:183], v[76:79]
	v_mfma_f32_16x16x32_bf16 v[40:43], v[148:151], v[188:191], v[40:43]
	v_mfma_f32_16x16x32_bf16 v[44:47], v[156:159], v[188:191], v[44:47]
	v_mfma_f32_16x16x32_bf16 v[24:27], v[148:151], v[202:205], v[24:27]
	v_mfma_f32_16x16x32_bf16 v[28:31], v[156:159], v[202:205], v[28:31]
	v_mfma_f32_16x16x32_bf16 v[8:11], v[148:151], v[210:213], v[8:11]
	v_mfma_f32_16x16x32_bf16 v[12:15], v[156:159], v[210:213], v[12:15]
	v_mfma_f32_16x16x32_bf16 v[68:71], v[152:155], v[184:187], v[68:71]
	v_mfma_f32_16x16x32_bf16 v[76:79], v[160:163], v[184:187], v[76:79]
	v_mfma_f32_16x16x32_bf16 v[40:43], v[152:155], v[198:201], v[40:43]
	v_mfma_f32_16x16x32_bf16 v[44:47], v[160:163], v[198:201], v[44:47]
	v_mfma_f32_16x16x32_bf16 v[24:27], v[152:155], v[206:209], v[24:27]
	v_mfma_f32_16x16x32_bf16 v[28:31], v[160:163], v[206:209], v[28:31]
	v_mfma_f32_16x16x32_bf16 v[8:11], v[152:155], v[230:233], v[8:11]
	v_mfma_f32_16x16x32_bf16 v[12:15], v[160:163], v[230:233], v[12:15]
	s_setprio 0
	s_setprio 1
	v_mfma_f32_16x16x32_bf16 v[120:123], v[164:167], v[180:183], v[120:123]
	v_mfma_f32_16x16x32_bf16 v[124:127], v[172:175], v[180:183], v[124:127]
	v_mfma_f32_16x16x32_bf16 v[104:107], v[164:167], v[188:191], v[104:107]
	v_mfma_f32_16x16x32_bf16 v[108:111], v[172:175], v[188:191], v[108:111]
	v_mfma_f32_16x16x32_bf16 v[88:91], v[164:167], v[202:205], v[88:91]
	v_mfma_f32_16x16x32_bf16 v[92:95], v[172:175], v[202:205], v[92:95]
	v_mfma_f32_16x16x32_bf16 v[60:63], v[164:167], v[210:213], v[60:63]
	v_mfma_f32_16x16x32_bf16 v[72:75], v[172:175], v[210:213], v[72:75]
	v_mfma_f32_16x16x32_bf16 v[120:123], v[168:171], v[184:187], v[120:123]
	v_mfma_f32_16x16x32_bf16 v[124:127], v[176:179], v[184:187], v[124:127]
	v_mfma_f32_16x16x32_bf16 v[104:107], v[168:171], v[198:201], v[104:107]
	v_mfma_f32_16x16x32_bf16 v[108:111], v[176:179], v[198:201], v[108:111]
	v_mfma_f32_16x16x32_bf16 v[88:91], v[168:171], v[206:209], v[88:91]
	v_mfma_f32_16x16x32_bf16 v[92:95], v[176:179], v[206:209], v[92:95]
	v_mfma_f32_16x16x32_bf16 v[60:63], v[168:171], v[230:233], v[60:63]
	v_mfma_f32_16x16x32_bf16 v[72:75], v[176:179], v[230:233], v[72:75]
	s_setprio 0
	s_barrier
	s_add_i32 s53, s53, s36
	v_lshl_add_u64 v[220:221], s[24:25], 0, v[136:137]
	s_mov_b32 m0, s53
	ds_read_b128 v[180:183], v146 offset:16384
	ds_read_b128 v[184:187], v146 offset:17408
	ds_read_b128 v[188:191], v146 offset:18432
	ds_read_b128 v[198:201], v146 offset:19456
	ds_read_b128 v[202:205], v146 offset:20480
	ds_read_b128 v[206:209], v146 offset:21504
	ds_read_b128 v[210:213], v146 offset:22528
	ds_read_b128 v[230:233], v146 offset:23552
	global_load_lds_dwordx4 v[220:221], off
	s_add_i32 m0, s53, 0x2000
	s_add_u32 s54, s24, 0x80000
	v_lshl_add_u64 v[222:223], s[24:25], 0, v[140:141]
	s_addc_u32 s55, s25, 0
	s_add_i32 s53, s58, s36
	global_load_lds_dwordx4 v[222:223], off
	v_lshl_add_u64 v[234:235], s[54:55], 0, v[136:137]
	s_mov_b32 m0, s53
	v_lshl_add_u64 v[236:237], s[26:27], 0, v[138:139]
	global_load_lds_dwordx4 v[234:235], off
	v_lshl_add_u64 v[234:235], s[54:55], 0, v[140:141]
	s_add_i32 m0, s53, 0x2000
	s_nop 0
	global_load_lds_dwordx4 v[234:235], off
	v_lshl_add_u64 v[234:235], s[26:27], 0, v[130:131]
	s_mov_b32 m0, s17
	s_nop 0
	global_load_lds_dwordx4 v[234:235], off
	s_mov_b32 m0, s37
	s_nop 0
	global_load_lds_dwordx4 v[236:237], off
	s_waitcnt vmcnt(8)
	s_waitcnt lgkmcnt(0)
	s_barrier
; #define PG8_STAGE(bufoff, gbase, voff) do { _Pragma("unroll") for (int _i = 0; _i < 2; ++_i) \
;         __builtin_amdgcn_global_load_lds((const unsigned*)((const char*)(gbase) + (voff)[_i]), (LAS unsigned*)(lds + (bufoff) + ldsw + _i * 8192), 16, 0, 0); } while (0)
; #define PG8_LDA(dst, b, h) do { _Pragma("unroll") for (int m = 0; m < 4; ++m) _Pragma("unroll") for (int k = 0; k < 2; ++k) dst[m][k] = *(const LAS bf16x8*)(lds + PG8_SA(b, h) + aoff + m * 2048 + k * 1024); } while (0)
; #define PG8_LDB(dst, b, h) do { _Pragma("unroll") for (int n = 0; n < 2; ++n) _Pragma("unroll") for (int k = 0; k < 2; ++k) dst[n][k] = *(const LAS bf16x8*)(lds + PG8_SB(b, h) + boff + n * 2048 + k * 1024); } while (0)
; #define PG8_MMA(ai, bj, At, Bt) do { __builtin_amdgcn_s_setprio(1); _Pragma("unroll") for (int m = 0; m < 4; ++m) _Pragma("unroll") for (int n = 0; n < 2; ++n) _Pragma("unroll") for (int k = 0; k < 2; ++k) \
;         acc[ai][bj][m][n] = __builtin_amdgcn_mfma_f32_16x16x32_bf16(Bt[n][k], At[m][k], acc[ai][bj][m][n], 0, 0, 0); __builtin_amdgcn_s_setprio(0); } while (0)
; #define PG8_WAIT_V(n) asm volatile("s_waitcnt vmcnt(" #n ")" ::: "memory")
; #define PG8_WAIT_L(n) asm volatile("s_waitcnt lgkmcnt(" #n ")" ::: "memory")
; #define PG8_BAR __builtin_amdgcn_s_barrier()
; #define PG8_SCHED __builtin_amdgcn_sched_barrier(0)
;     ...
;             PG8_WAIT_V(8); PG8_WAIT_L(0); PG8_BAR; PG8_MMA(0, 0, At, B0); PG8_MMA(0, 1, At, B1); PG8_BAR; PG8_SCHED;
;             PG8_LDA(At, 0, 1); PG8_STAGE(PG8_SB(0, 0), b2, voffB); PG8_STAGE(PG8_SB(0, 1), b2 + hstepB, voffB); PG8_STAGE(PG8_SA(0, 0), a2, voffA);
;             PG8_WAIT_V(8); PG8_WAIT_L(0); PG8_BAR; PG8_MMA(1, 0, At, B0); PG8_MMA(1, 1, At, B1); PG8_BAR; PG8_SCHED;
;             PG8_LDB(B0, 1, 0); PG8_LDB(B1, 1, 1); PG8_SCHED; PG8_LDA(At, 1, 0); PG8_STAGE(PG8_SA(0, 1), a2 + hstepA, voffA);
;             PG8_WAIT_V(8); PG8_WAIT_L(0); PG8_BAR; PG8_MMA(0, 0, At, B0); PG8_MMA(0, 1, At, B1); PG8_BAR; PG8_SCHED;
;             PG8_LDA(At, 1, 1); PG8_STAGE(PG8_SB(1, 0), b3, voffB); PG8_STAGE(PG8_SB(1, 1), b3 + hstepB, voffB); PG8_STAGE(PG8_SA(1, 0), a3, voffA);
;             PG8_WAIT_V(8); PG8_WAIT_L(0); PG8_BAR; PG8_MMA(1, 0, At, B0); PG8_MMA(1, 1, At, B1); PG8_BAR; PG8_SCHED;
	s_setprio 1
	s_waitcnt lgkmcnt(0)
	v_mfma_f32_16x16x32_bf16 v[52:55], v[148:151], v[180:183], v[52:55]
	v_mfma_f32_16x16x32_bf16 v[64:67], v[156:159], v[180:183], v[64:67]
	v_mfma_f32_16x16x32_bf16 v[32:35], v[148:151], v[188:191], v[32:35]
	v_mfma_f32_16x16x32_bf16 v[36:39], v[156:159], v[188:191], v[36:39]
	v_mfma_f32_16x16x32_bf16 v[16:19], v[148:151], v[202:205], v[16:19]
	v_mfma_f32_16x16x32_bf16 v[20:23], v[156:159], v[202:205], v[20:23]
	v_mfma_f32_16x16x32_bf16 v[0:3], v[148:151], v[210:213], v[0:3]
	v_mfma_f32_16x16x32_bf16 v[4:7], v[156:159], v[210:213], v[4:7]
	v_mfma_f32_16x16x32_bf16 v[52:55], v[152:155], v[184:187], v[52:55]
	v_mfma_f32_16x16x32_bf16 v[64:67], v[160:163], v[184:187], v[64:67]
	v_mfma_f32_16x16x32_bf16 v[32:35], v[152:155], v[198:201], v[32:35]
	v_mfma_f32_16x16x32_bf16 v[36:39], v[160:163], v[198:201], v[36:39]
	v_mfma_f32_16x16x32_bf16 v[16:19], v[152:155], v[206:209], v[16:19]
	v_mfma_f32_16x16x32_bf16 v[20:23], v[160:163], v[206:209], v[20:23]
	v_mfma_f32_16x16x32_bf16 v[0:3], v[152:155], v[230:233], v[0:3]
	v_mfma_f32_16x16x32_bf16 v[4:7], v[160:163], v[230:233], v[4:7]
	s_setprio 0
	s_setprio 1
	v_mfma_f32_16x16x32_bf16 v[112:115], v[164:167], v[180:183], v[112:115]
	v_mfma_f32_16x16x32_bf16 v[116:119], v[172:175], v[180:183], v[116:119]
	v_mfma_f32_16x16x32_bf16 v[96:99], v[164:167], v[188:191], v[96:99]
	v_mfma_f32_16x16x32_bf16 v[100:103], v[172:175], v[188:191], v[100:103]
	v_mfma_f32_16x16x32_bf16 v[80:83], v[164:167], v[202:205], v[80:83]
	v_mfma_f32_16x16x32_bf16 v[84:87], v[172:175], v[202:205], v[84:87]
	v_mfma_f32_16x16x32_bf16 v[48:51], v[164:167], v[210:213], v[48:51]
	v_mfma_f32_16x16x32_bf16 v[56:59], v[172:175], v[210:213], v[56:59]
	v_mfma_f32_16x16x32_bf16 v[112:115], v[168:171], v[184:187], v[112:115]
	v_mfma_f32_16x16x32_bf16 v[116:119], v[176:179], v[184:187], v[116:119]
	v_mfma_f32_16x16x32_bf16 v[96:99], v[168:171], v[198:201], v[96:99]
	v_mfma_f32_16x16x32_bf16 v[100:103], v[176:179], v[198:201], v[100:103]
	v_mfma_f32_16x16x32_bf16 v[80:83], v[168:171], v[206:209], v[80:83]
	v_mfma_f32_16x16x32_bf16 v[84:87], v[176:179], v[206:209], v[84:87]
	v_mfma_f32_16x16x32_bf16 v[48:51], v[168:171], v[230:233], v[48:51]
	v_mfma_f32_16x16x32_bf16 v[56:59], v[176:179], v[230:233], v[56:59]
	s_setprio 0
	s_barrier
	s_add_i32 s53, 0, 0x18000
	v_add_u32_e32 v147, s53, v129
	s_add_i32 s54, 0, 0x1c000
	ds_read_b128 v[148:151], v147
	ds_read_b128 v[152:155], v147 offset:1024
	ds_read_b128 v[156:159], v147 offset:2048
	ds_read_b128 v[160:163], v147 offset:3072
	v_add_u32_e32 v147, s54, v129
	ds_read_b128 v[164:167], v147
	ds_read_b128 v[168:171], v147 offset:1024
	ds_read_b128 v[172:175], v147 offset:2048
	ds_read_b128 v[176:179], v147 offset:3072
	s_add_u32 s26, s26, 0x80000
	s_addc_u32 s27, s27, 0
	s_mov_b32 m0, s38
	v_lshl_add_u64 v[238:239], s[26:27], 0, v[130:131]
	ds_read_b128 v[180:183], v146 offset:32768
	ds_read_b128 v[184:187], v146 offset:33792
	ds_read_b128 v[188:191], v146 offset:34816
	ds_read_b128 v[198:201], v146 offset:35840
	ds_read_b128 v[202:205], v146 offset:36864
	ds_read_b128 v[206:209], v146 offset:37888
	ds_read_b128 v[210:213], v146 offset:38912
	ds_read_b128 v[230:233], v146 offset:39936
	global_load_lds_dwordx4 v[238:239], off
	v_lshl_add_u64 v[238:239], s[26:27], 0, v[138:139]
	s_mov_b32 m0, s39
	s_nop 0
	global_load_lds_dwordx4 v[238:239], off
	s_waitcnt vmcnt(8)
	s_waitcnt lgkmcnt(0)
	s_barrier
	s_setprio 1
	s_waitcnt lgkmcnt(0)
	v_mfma_f32_16x16x32_bf16 v[68:71], v[148:151], v[180:183], v[68:71]
	v_mfma_f32_16x16x32_bf16 v[76:79], v[156:159], v[180:183], v[76:79]
	v_mfma_f32_16x16x32_bf16 v[40:43], v[148:151], v[188:191], v[40:43]
	v_mfma_f32_16x16x32_bf16 v[44:47], v[156:159], v[188:191], v[44:47]
	v_mfma_f32_16x16x32_bf16 v[24:27], v[148:151], v[202:205], v[24:27]
	v_mfma_f32_16x16x32_bf16 v[28:31], v[156:159], v[202:205], v[28:31]
	v_mfma_f32_16x16x32_bf16 v[8:11], v[148:151], v[210:213], v[8:11]
	v_mfma_f32_16x16x32_bf16 v[12:15], v[156:159], v[210:213], v[12:15]
	v_mfma_f32_16x16x32_bf16 v[68:71], v[152:155], v[184:187], v[68:71]
	v_mfma_f32_16x16x32_bf16 v[76:79], v[160:163], v[184:187], v[76:79]
	v_mfma_f32_16x16x32_bf16 v[40:43], v[152:155], v[198:201], v[40:43]
	v_mfma_f32_16x16x32_bf16 v[44:47], v[160:163], v[198:201], v[44:47]
	v_mfma_f32_16x16x32_bf16 v[24:27], v[152:155], v[206:209], v[24:27]
	v_mfma_f32_16x16x32_bf16 v[28:31], v[160:163], v[206:209], v[28:31]
	v_mfma_f32_16x16x32_bf16 v[8:11], v[152:155], v[230:233], v[8:11]
	v_mfma_f32_16x16x32_bf16 v[12:15], v[160:163], v[230:233], v[12:15]
	s_setprio 0
	s_setprio 1
	v_mfma_f32_16x16x32_bf16 v[120:123], v[164:167], v[180:183], v[120:123]
	v_mfma_f32_16x16x32_bf16 v[124:127], v[172:175], v[180:183], v[124:127]
	v_mfma_f32_16x16x32_bf16 v[104:107], v[164:167], v[188:191], v[104:107]
	v_mfma_f32_16x16x32_bf16 v[108:111], v[172:175], v[188:191], v[108:111]
	v_mfma_f32_16x16x32_bf16 v[88:91], v[164:167], v[202:205], v[88:91]
	v_mfma_f32_16x16x32_bf16 v[92:95], v[172:175], v[202:205], v[92:95]
	v_mfma_f32_16x16x32_bf16 v[60:63], v[164:167], v[210:213], v[60:63]
	v_mfma_f32_16x16x32_bf16 v[72:75], v[172:175], v[210:213], v[72:75]
	v_mfma_f32_16x16x32_bf16 v[120:123], v[168:171], v[184:187], v[120:123]
	v_mfma_f32_16x16x32_bf16 v[124:127], v[176:179], v[184:187], v[124:127]
	v_mfma_f32_16x16x32_bf16 v[104:107], v[168:171], v[198:201], v[104:107]
	v_mfma_f32_16x16x32_bf16 v[108:111], v[176:179], v[198:201], v[108:111]
	v_mfma_f32_16x16x32_bf16 v[88:91], v[168:171], v[206:209], v[88:91]
	v_mfma_f32_16x16x32_bf16 v[92:95], v[176:179], v[206:209], v[92:95]
	v_mfma_f32_16x16x32_bf16 v[60:63], v[168:171], v[230:233], v[60:63]
	v_mfma_f32_16x16x32_bf16 v[72:75], v[176:179], v[230:233], v[72:75]
	s_setprio 0
	s_barrier
; #define PG8_STAGE(bufoff, gbase, voff) do { _Pragma("unroll") for (int _i = 0; _i < 2; ++_i) \
;         __builtin_amdgcn_global_load_lds((const unsigned*)((const char*)(gbase) + (voff)[_i]), (LAS unsigned*)(lds + (bufoff) + ldsw + _i * 8192), 16, 0, 0); } while (0)
; #define PG8_LDA(dst, b, h) do { _Pragma("unroll") for (int m = 0; m < 4; ++m) _Pragma("unroll") for (int k = 0; k < 2; ++k) dst[m][k] = *(const LAS bf16x8*)(lds + PG8_SA(b, h) + aoff + m * 2048 + k * 1024); } while (0)
; #define PG8_MMA(ai, bj, At, Bt) do { __builtin_amdgcn_s_setprio(1); _Pragma("unroll") for (int m = 0; m < 4; ++m) _Pragma("unroll") for (int n = 0; n < 2; ++n) _Pragma("unroll") for (int k = 0; k < 2; ++k) \
;         acc[ai][bj][m][n] = __builtin_amdgcn_mfma_f32_16x16x32_bf16(Bt[n][k], At[m][k], acc[ai][bj][m][n], 0, 0, 0); __builtin_amdgcn_s_setprio(0); } while (0)
; #define PG8_WAIT_V(n) asm volatile("s_waitcnt vmcnt(" #n ")" ::: "memory")
; #define PG8_WAIT_L(n) asm volatile("s_waitcnt lgkmcnt(" #n ")" ::: "memory")
; #define PG8_BAR __builtin_amdgcn_s_barrier()
; #define PG8_SCHED __builtin_amdgcn_sched_barrier(0)
;     ...
;             PG8_LDA(At, 1, 1); PG8_STAGE(PG8_SB(1, 0), b3, voffB); PG8_STAGE(PG8_SB(1, 1), b3 + hstepB, voffB); PG8_STAGE(PG8_SA(1, 0), a3, voffA);
;             PG8_WAIT_V(8); PG8_WAIT_L(0); PG8_BAR; PG8_MMA(1, 0, At, B0); PG8_MMA(1, 1, At, B1); PG8_BAR; PG8_SCHED;
;             if constexpr (MIDK > 0) { if (((t + 2) % MIDK) == 0 && t + 2 < nt) { int ln_; asm volatile("v_mbcnt_lo_u32_b32 %0, -1, 0\n\tv_mbcnt_hi_u32_b32 %0, -1, %0" : "=v"(ln_)); E.mid(acc, cur, (t + 2) / MIDK - 1, wr, wc, ln_ & 15, ln_ >> 4); } }
;         }
	s_add_i32 s26, s53, s36
	v_lshl_add_u64 v[220:221], v[220:221], 0, s[78:79]
	s_mov_b32 m0, s26
	ds_read_b128 v[180:183], v146 offset:49152
	ds_read_b128 v[184:187], v146 offset:50176
	ds_read_b128 v[188:191], v146 offset:51200
	ds_read_b128 v[198:201], v146 offset:52224
	ds_read_b128 v[202:205], v146 offset:53248
	ds_read_b128 v[206:209], v146 offset:54272
	ds_read_b128 v[210:213], v146 offset:55296
	ds_read_b128 v[230:233], v146 offset:56320
	global_load_lds_dwordx4 v[220:221], off
	s_add_i32 m0, s26, 0x2000
	s_add_u32 s24, s24, 0x80080
	v_lshl_add_u64 v[220:221], v[222:223], 0, s[78:79]
	s_addc_u32 s25, s25, 0
	s_add_i32 s26, s54, s36
	global_load_lds_dwordx4 v[220:221], off
	v_lshl_add_u64 v[220:221], s[24:25], 0, v[136:137]
	s_mov_b32 m0, s26
	s_nop 0
	global_load_lds_dwordx4 v[220:221], off
	v_lshl_add_u64 v[220:221], s[24:25], 0, v[140:141]
	s_add_i32 m0, s26, 0x2000
	s_nop 0
	global_load_lds_dwordx4 v[220:221], off
	v_lshl_add_u64 v[220:221], v[234:235], 0, s[78:79]
	s_mov_b32 m0, s42
	s_nop 0
	global_load_lds_dwordx4 v[220:221], off
	v_lshl_add_u64 v[220:221], v[236:237], 0, s[78:79]
	s_mov_b32 m0, s43
	s_nop 0
	global_load_lds_dwordx4 v[220:221], off
	s_waitcnt vmcnt(8)
	s_waitcnt lgkmcnt(0)
	s_barrier
	s_setprio 1
	s_waitcnt lgkmcnt(0)
	v_mfma_f32_16x16x32_bf16 v[52:55], v[148:151], v[180:183], v[52:55]
	v_mfma_f32_16x16x32_bf16 v[64:67], v[156:159], v[180:183], v[64:67]
	v_mfma_f32_16x16x32_bf16 v[32:35], v[148:151], v[188:191], v[32:35]
	v_mfma_f32_16x16x32_bf16 v[36:39], v[156:159], v[188:191], v[36:39]
	v_mfma_f32_16x16x32_bf16 v[16:19], v[148:151], v[202:205], v[16:19]
	v_mfma_f32_16x16x32_bf16 v[20:23], v[156:159], v[202:205], v[20:23]
	v_mfma_f32_16x16x32_bf16 v[0:3], v[148:151], v[210:213], v[0:3]
	v_mfma_f32_16x16x32_bf16 v[4:7], v[156:159], v[210:213], v[4:7]
	v_mfma_f32_16x16x32_bf16 v[52:55], v[152:155], v[184:187], v[52:55]
	v_mfma_f32_16x16x32_bf16 v[64:67], v[160:163], v[184:187], v[64:67]
	v_mfma_f32_16x16x32_bf16 v[32:35], v[152:155], v[198:201], v[32:35]
	v_mfma_f32_16x16x32_bf16 v[36:39], v[160:163], v[198:201], v[36:39]
	v_mfma_f32_16x16x32_bf16 v[16:19], v[152:155], v[206:209], v[16:19]
	v_mfma_f32_16x16x32_bf16 v[20:23], v[160:163], v[206:209], v[20:23]
	v_mfma_f32_16x16x32_bf16 v[0:3], v[152:155], v[230:233], v[0:3]
	v_mfma_f32_16x16x32_bf16 v[4:7], v[160:163], v[230:233], v[4:7]
	s_setprio 0
	s_setprio 1
	v_mfma_f32_16x16x32_bf16 v[112:115], v[164:167], v[180:183], v[112:115]
	v_mfma_f32_16x16x32_bf16 v[116:119], v[172:175], v[180:183], v[116:119]
	v_mfma_f32_16x16x32_bf16 v[96:99], v[164:167], v[188:191], v[96:99]
	v_mfma_f32_16x16x32_bf16 v[100:103], v[172:175], v[188:191], v[100:103]
	v_mfma_f32_16x16x32_bf16 v[80:83], v[164:167], v[202:205], v[80:83]
	v_mfma_f32_16x16x32_bf16 v[84:87], v[172:175], v[202:205], v[84:87]
	v_mfma_f32_16x16x32_bf16 v[48:51], v[164:167], v[210:213], v[48:51]
	v_mfma_f32_16x16x32_bf16 v[56:59], v[172:175], v[210:213], v[56:59]
	v_mfma_f32_16x16x32_bf16 v[112:115], v[168:171], v[184:187], v[112:115]
	v_mfma_f32_16x16x32_bf16 v[116:119], v[176:179], v[184:187], v[116:119]
	v_mfma_f32_16x16x32_bf16 v[96:99], v[168:171], v[198:201], v[96:99]
	v_mfma_f32_16x16x32_bf16 v[100:103], v[176:179], v[198:201], v[100:103]
	v_mfma_f32_16x16x32_bf16 v[80:83], v[168:171], v[206:209], v[80:83]
	v_mfma_f32_16x16x32_bf16 v[84:87], v[176:179], v[206:209], v[84:87]
	v_mfma_f32_16x16x32_bf16 v[48:51], v[168:171], v[230:233], v[48:51]
	v_mfma_f32_16x16x32_bf16 v[56:59], v[176:179], v[230:233], v[56:59]
	s_setprio 0
	s_barrier
	s_add_u32 s50, s50, 0x100
	s_addc_u32 s51, s51, 0
	s_add_u32 s22, s22, 0x100
	s_addc_u32 s23, s23, 0
	s_cmp_ge_i32 s52, s28
	s_mov_b32 s24, s52
	s_cbranch_scc0 .LBB0_309
	s_nop 0
	s_nop 0
	s_nop 0
	s_nop 0
	s_nop 0
	s_nop 0
	s_nop 0
	s_nop 0
	s_nop 0
	s_nop 0
	s_nop 0
	s_nop 0
	s_mov_b32 s58, 0x90000
